# v43 + in-proj/out-proj K-loops: pointer-advance and exit-test SALU block moved ahead of the loop-back barrier (back-edge rotation)
# baseline (speedup 1.0000x reference)
; #define PG8_STAGE(bufoff, gbase, voff) do { _Pragma("unroll") for (int _i = 0; _i < 2; ++_i) \
;         __builtin_amdgcn_global_load_lds((const unsigned*)((const char*)(gbase) + (voff)[_i]), (LAS unsigned*)(lds + (bufoff) + ldsw + _i * 8192), 16, 0, 0); } while (0)
; #define PG8_LDA(dst, b, h) do { _Pragma("unroll") for (int m = 0; m < 4; ++m) _Pragma("unroll") for (int k = 0; k < 2; ++k) dst[m][k] = *(const LAS bf16x8*)(lds + PG8_SA(b, h) + aoff + m * 2048 + k * 1024); } while (0)
; #define PG8_LDB(dst, b, h) do { _Pragma("unroll") for (int n = 0; n < 2; ++n) _Pragma("unroll") for (int k = 0; k < 2; ++k) dst[n][k] = *(const LAS bf16x8*)(lds + PG8_SB(b, h) + boff + n * 2048 + k * 1024); } while (0)
; #define PG8_MMA(ai, bj, At, Bt) do { __builtin_amdgcn_s_setprio(1); _Pragma("unroll") for (int m = 0; m < 4; ++m) _Pragma("unroll") for (int n = 0; n < 2; ++n) _Pragma("unroll") for (int k = 0; k < 2; ++k) \
;         acc[ai][bj][m][n] = __builtin_amdgcn_mfma_f32_16x16x32_bf16(Bt[n][k], At[m][k], acc[ai][bj][m][n], 0, 0, 0); __builtin_amdgcn_s_setprio(0); } while (0)
; #define PG8_WAIT_V(n) asm volatile("s_waitcnt vmcnt(" #n ")" ::: "memory")
; #define PG8_WAIT_L(n) asm volatile("s_waitcnt lgkmcnt(" #n ")" ::: "memory")
; #define PG8_BAR __builtin_amdgcn_s_barrier()
; #define PG8_SCHED __builtin_amdgcn_sched_barrier(0)
; template <class Epi, class Sched, bool HALFN = false>
; __device__ __forceinline__ void gemm_phase(LAS unsigned char* lds, const Gemm g, const Sched& S, const Epi& E, int wave_s) {
;     ...
;         for (int t = 0; t < nt; t += 2) {
;             const bool last = (t == nt - 2);
;             const char* a1 = cA + (size_t)(t + 1) * kstep;
;             const char* a2 = last ? nA : cA + (size_t)(t + 2) * kstep; const char* b2 = last ? nB : cB + (size_t)(t + 2) * kstep;
;             const char* a3 = a2 + kstep; const char* b3 = b2 + kstep;
;             PG8_LDB(B0, 0, 0); if (!HALFN) PG8_LDB(B1, 0, 1); PG8_SCHED; PG8_LDA(At, 0, 0); PG8_STAGE(PG8_SA(1, 1), a1 + hstep, voffA);
;             PG8_WAIT_V(8); PG8_WAIT_L(0); PG8_BAR; PG8_MMA(0, 0, At, B0); if (!HALFN) PG8_MMA(0, 1, At, B1); PG8_BAR; PG8_SCHED;
;             PG8_LDA(At, 0, 1); PG8_STAGE(PG8_SB(0, 0), b2, voffB); PG8_STAGE(PG8_SB(0, 1), b2 + bh1, voffB); PG8_STAGE(PG8_SA(0, 0), a2, voffA);
.LBB0_269:
	s_add_u32 s53, s8, 0xfffc0080
	s_addc_u32 s66, s9, -1
	s_add_i32 s82, 0, 0x10000
	s_cmp_eq_u32 s52, 12
	s_cselect_b32 s81, s5, s66
	s_cselect_b32 s80, s7, s53
	v_add_u32_e32 v18, s82, v1
	s_cselect_b32 s79, s39, s48
	s_cselect_b32 s78, s42, s47
	s_add_i32 s53, 0, 0x14000
	ds_read_b128 v[146:149], v18
	ds_read_b128 v[150:153], v18 offset:1024
	ds_read_b128 v[154:157], v18 offset:2048
	ds_read_b128 v[158:161], v18 offset:3072
	v_add_u32_e32 v18, s53, v1
	ds_read_b128 v[162:165], v18
	ds_read_b128 v[166:169], v18 offset:1024
	ds_read_b128 v[172:175], v18 offset:2048
	ds_read_b128 v[176:179], v18 offset:3072
	v_lshl_add_u64 v[196:197], s[8:9], 0, v[140:141]
	s_add_i32 m0, s67, 0xc000
	ds_read_b128 v[180:183], v170
	ds_read_b128 v[184:187], v170 offset:1024
	ds_read_b128 v[188:191], v170 offset:2048
	ds_read_b128 v[192:195], v170 offset:3072
	ds_read_b128 v[208:211], v170 offset:4096
	ds_read_b128 v[212:215], v170 offset:5120
	ds_read_b128 v[216:219], v170 offset:6144
	ds_read_b128 v[220:223], v170 offset:7168
	global_load_lds_dwordx4 v[196:197], off
	v_lshl_add_u64 v[196:197], s[8:9], 0, v[142:143]
	s_add_i32 m0, s67, 0xe000
	s_nop 0
	global_load_lds_dwordx4 v[196:197], off
	s_waitcnt vmcnt(8)
	s_waitcnt lgkmcnt(0)
	s_barrier
	s_setprio 1
	s_waitcnt lgkmcnt(0)
	v_mfma_f32_16x16x32_bf16 v[128:131], v[146:149], v[180:183], v[128:131]
	v_mfma_f32_16x16x32_bf16 v[124:127], v[154:157], v[180:183], v[124:127]
	v_mfma_f32_16x16x32_bf16 v[112:115], v[146:149], v[188:191], v[112:115]
	v_mfma_f32_16x16x32_bf16 v[108:111], v[154:157], v[188:191], v[108:111]
	v_mfma_f32_16x16x32_bf16 v[96:99], v[146:149], v[208:211], v[96:99]
	v_mfma_f32_16x16x32_bf16 v[92:95], v[154:157], v[208:211], v[92:95]
	v_mfma_f32_16x16x32_bf16 v[80:83], v[146:149], v[216:219], v[80:83]
	v_mfma_f32_16x16x32_bf16 v[76:79], v[154:157], v[216:219], v[76:79]
	v_mfma_f32_16x16x32_bf16 v[128:131], v[150:153], v[184:187], v[128:131]
	v_mfma_f32_16x16x32_bf16 v[124:127], v[158:161], v[184:187], v[124:127]
	v_mfma_f32_16x16x32_bf16 v[112:115], v[150:153], v[192:195], v[112:115]
	v_mfma_f32_16x16x32_bf16 v[108:111], v[158:161], v[192:195], v[108:111]
	v_mfma_f32_16x16x32_bf16 v[96:99], v[150:153], v[212:215], v[96:99]
	v_mfma_f32_16x16x32_bf16 v[92:95], v[158:161], v[212:215], v[92:95]
	v_mfma_f32_16x16x32_bf16 v[80:83], v[150:153], v[220:223], v[80:83]
	v_mfma_f32_16x16x32_bf16 v[76:79], v[158:161], v[220:223], v[76:79]
	v_mfma_f32_16x16x32_bf16 v[120:123], v[162:165], v[180:183], v[120:123]
	v_mfma_f32_16x16x32_bf16 v[116:119], v[172:175], v[180:183], v[116:119]
	v_mfma_f32_16x16x32_bf16 v[104:107], v[162:165], v[188:191], v[104:107]
	v_mfma_f32_16x16x32_bf16 v[100:103], v[172:175], v[188:191], v[100:103]
	v_mfma_f32_16x16x32_bf16 v[88:91], v[162:165], v[208:211], v[88:91]
	v_mfma_f32_16x16x32_bf16 v[84:87], v[172:175], v[208:211], v[84:87]
	v_mfma_f32_16x16x32_bf16 v[72:75], v[162:165], v[216:219], v[72:75]
	v_mfma_f32_16x16x32_bf16 v[68:71], v[172:175], v[216:219], v[68:71]
	v_mfma_f32_16x16x32_bf16 v[120:123], v[166:169], v[184:187], v[120:123]
	v_mfma_f32_16x16x32_bf16 v[116:119], v[176:179], v[184:187], v[116:119]
	v_mfma_f32_16x16x32_bf16 v[104:107], v[166:169], v[192:195], v[104:107]
	v_mfma_f32_16x16x32_bf16 v[100:103], v[176:179], v[192:195], v[100:103]
	v_mfma_f32_16x16x32_bf16 v[88:91], v[166:169], v[212:215], v[88:91]
	v_mfma_f32_16x16x32_bf16 v[84:87], v[176:179], v[212:215], v[84:87]
	v_mfma_f32_16x16x32_bf16 v[72:75], v[166:169], v[220:223], v[72:75]
	v_mfma_f32_16x16x32_bf16 v[68:71], v[176:179], v[220:223], v[68:71]
	s_setprio 0
	s_barrier
	s_add_i32 s66, s82, s64
	v_lshl_add_u64 v[196:197], s[78:79], 0, v[134:135]
	s_mov_b32 m0, s66
	ds_read_b128 v[180:183], v170 offset:16384
	ds_read_b128 v[184:187], v170 offset:17408
	ds_read_b128 v[188:191], v170 offset:18432
	ds_read_b128 v[192:195], v170 offset:19456
	ds_read_b128 v[208:211], v170 offset:20480
	ds_read_b128 v[212:215], v170 offset:21504
	ds_read_b128 v[216:219], v170 offset:22528
	ds_read_b128 v[220:223], v170 offset:23552
	global_load_lds_dwordx4 v[196:197], off
	s_add_i32 m0, s66, 0x2000
	s_add_u32 s82, s78, 0x40000
	v_lshl_add_u64 v[224:225], s[78:79], 0, v[138:139]
	s_addc_u32 s83, s79, 0
	s_add_i32 s53, s53, s64
	global_load_lds_dwordx4 v[224:225], off
	v_lshl_add_u64 v[226:227], s[82:83], 0, v[134:135]
	s_mov_b32 m0, s53
	v_lshl_add_u64 v[228:229], s[80:81], 0, v[136:137]
	global_load_lds_dwordx4 v[226:227], off
	v_lshl_add_u64 v[226:227], s[82:83], 0, v[138:139]
	s_add_i32 m0, s53, 0x2000
	s_nop 0
	global_load_lds_dwordx4 v[226:227], off
	v_lshl_add_u64 v[226:227], s[80:81], 0, v[132:133]
	s_mov_b32 m0, s67
	s_nop 0
	global_load_lds_dwordx4 v[226:227], off
	s_mov_b32 m0, s70
	s_nop 0
	global_load_lds_dwordx4 v[228:229], off
	s_waitcnt vmcnt(8)
	s_waitcnt lgkmcnt(0)
	s_barrier
; #define PG8_STAGE(bufoff, gbase, voff) do { _Pragma("unroll") for (int _i = 0; _i < 2; ++_i) \
;         __builtin_amdgcn_global_load_lds((const unsigned*)((const char*)(gbase) + (voff)[_i]), (LAS unsigned*)(lds + (bufoff) + ldsw + _i * 8192), 16, 0, 0); } while (0)
; #define PG8_LDA(dst, b, h) do { _Pragma("unroll") for (int m = 0; m < 4; ++m) _Pragma("unroll") for (int k = 0; k < 2; ++k) dst[m][k] = *(const LAS bf16x8*)(lds + PG8_SA(b, h) + aoff + m * 2048 + k * 1024); } while (0)
; #define PG8_LDB(dst, b, h) do { _Pragma("unroll") for (int n = 0; n < 2; ++n) _Pragma("unroll") for (int k = 0; k < 2; ++k) dst[n][k] = *(const LAS bf16x8*)(lds + PG8_SB(b, h) + boff + n * 2048 + k * 1024); } while (0)
; #define PG8_MMA(ai, bj, At, Bt) do { __builtin_amdgcn_s_setprio(1); _Pragma("unroll") for (int m = 0; m < 4; ++m) _Pragma("unroll") for (int n = 0; n < 2; ++n) _Pragma("unroll") for (int k = 0; k < 2; ++k) \
;         acc[ai][bj][m][n] = __builtin_amdgcn_mfma_f32_16x16x32_bf16(Bt[n][k], At[m][k], acc[ai][bj][m][n], 0, 0, 0); __builtin_amdgcn_s_setprio(0); } while (0)
; #define PG8_WAIT_V(n) asm volatile("s_waitcnt vmcnt(" #n ")" ::: "memory")
; #define PG8_WAIT_L(n) asm volatile("s_waitcnt lgkmcnt(" #n ")" ::: "memory")
; #define PG8_BAR __builtin_amdgcn_s_barrier()
; #define PG8_SCHED __builtin_amdgcn_sched_barrier(0)
; template <class Epi, class Sched, bool HALFN = false>
; __device__ __forceinline__ void gemm_phase(LAS unsigned char* lds, const Gemm g, const Sched& S, const Epi& E, int wave_s) {
;     ...
;             PG8_WAIT_V(8); PG8_WAIT_L(0); PG8_BAR; PG8_MMA(1, 0, At, B0); if (!HALFN) PG8_MMA(1, 1, At, B1); PG8_BAR; PG8_SCHED;
;             PG8_LDB(B0, 1, 0); if (!HALFN) PG8_LDB(B1, 1, 1); PG8_SCHED; PG8_LDA(At, 1, 0); PG8_STAGE(PG8_SA(0, 1), a2 + hstep, voffA);
;             PG8_WAIT_V(8); PG8_WAIT_L(0); PG8_BAR; PG8_MMA(0, 0, At, B0); if (!HALFN) PG8_MMA(0, 1, At, B1); PG8_BAR; PG8_SCHED;
	s_setprio 1
	s_waitcnt lgkmcnt(0)
	v_mfma_f32_16x16x32_bf16 v[64:67], v[146:149], v[180:183], v[64:67]
	v_mfma_f32_16x16x32_bf16 v[60:63], v[154:157], v[180:183], v[60:63]
	v_mfma_f32_16x16x32_bf16 v[48:51], v[146:149], v[188:191], v[48:51]
	v_mfma_f32_16x16x32_bf16 v[44:47], v[154:157], v[188:191], v[44:47]
	v_mfma_f32_16x16x32_bf16 v[32:35], v[146:149], v[208:211], v[32:35]
	v_mfma_f32_16x16x32_bf16 v[28:31], v[154:157], v[208:211], v[28:31]
	v_mfma_f32_16x16x32_bf16 v[14:17], v[146:149], v[216:219], v[14:17]
	v_mfma_f32_16x16x32_bf16 v[10:13], v[154:157], v[216:219], v[10:13]
	v_mfma_f32_16x16x32_bf16 v[64:67], v[150:153], v[184:187], v[64:67]
	v_mfma_f32_16x16x32_bf16 v[60:63], v[158:161], v[184:187], v[60:63]
	v_mfma_f32_16x16x32_bf16 v[48:51], v[150:153], v[192:195], v[48:51]
	v_mfma_f32_16x16x32_bf16 v[44:47], v[158:161], v[192:195], v[44:47]
	v_mfma_f32_16x16x32_bf16 v[32:35], v[150:153], v[212:215], v[32:35]
	v_mfma_f32_16x16x32_bf16 v[28:31], v[158:161], v[212:215], v[28:31]
	v_mfma_f32_16x16x32_bf16 v[14:17], v[150:153], v[220:223], v[14:17]
	v_mfma_f32_16x16x32_bf16 v[10:13], v[158:161], v[220:223], v[10:13]
	v_mfma_f32_16x16x32_bf16 v[56:59], v[162:165], v[180:183], v[56:59]
	v_mfma_f32_16x16x32_bf16 v[52:55], v[172:175], v[180:183], v[52:55]
	v_mfma_f32_16x16x32_bf16 v[40:43], v[162:165], v[188:191], v[40:43]
	v_mfma_f32_16x16x32_bf16 v[36:39], v[172:175], v[188:191], v[36:39]
	v_mfma_f32_16x16x32_bf16 v[24:27], v[162:165], v[208:211], v[24:27]
	v_mfma_f32_16x16x32_bf16 v[20:23], v[172:175], v[208:211], v[20:23]
	v_mfma_f32_16x16x32_bf16 v[6:9], v[162:165], v[216:219], v[6:9]
	v_mfma_f32_16x16x32_bf16 v[2:5], v[172:175], v[216:219], v[2:5]
	v_mfma_f32_16x16x32_bf16 v[56:59], v[166:169], v[184:187], v[56:59]
	v_mfma_f32_16x16x32_bf16 v[52:55], v[176:179], v[184:187], v[52:55]
	v_mfma_f32_16x16x32_bf16 v[40:43], v[166:169], v[192:195], v[40:43]
	v_mfma_f32_16x16x32_bf16 v[36:39], v[176:179], v[192:195], v[36:39]
	v_mfma_f32_16x16x32_bf16 v[24:27], v[166:169], v[212:215], v[24:27]
	v_mfma_f32_16x16x32_bf16 v[20:23], v[176:179], v[212:215], v[20:23]
	v_mfma_f32_16x16x32_bf16 v[6:9], v[166:169], v[220:223], v[6:9]
	v_mfma_f32_16x16x32_bf16 v[2:5], v[176:179], v[220:223], v[2:5]
	s_setprio 0
	s_barrier
	s_add_i32 s53, 0, 0x18000
	v_add_u32_e32 v18, s53, v1
	s_add_i32 s66, 0, 0x1c000
	ds_read_b128 v[146:149], v18
	ds_read_b128 v[150:153], v18 offset:1024
	ds_read_b128 v[154:157], v18 offset:2048
	ds_read_b128 v[158:161], v18 offset:3072
	v_add_u32_e32 v18, s66, v1
	ds_read_b128 v[162:165], v18
	ds_read_b128 v[166:169], v18 offset:1024
	ds_read_b128 v[172:175], v18 offset:2048
	ds_read_b128 v[176:179], v18 offset:3072
	s_add_u32 s80, s80, 0x40000
	s_addc_u32 s81, s81, 0
	s_mov_b32 m0, s71
	v_lshl_add_u64 v[230:231], s[80:81], 0, v[132:133]
	ds_read_b128 v[180:183], v170 offset:32768
	ds_read_b128 v[184:187], v170 offset:33792
	ds_read_b128 v[188:191], v170 offset:34816
	ds_read_b128 v[192:195], v170 offset:35840
	ds_read_b128 v[208:211], v170 offset:36864
	ds_read_b128 v[212:215], v170 offset:37888
	ds_read_b128 v[216:219], v170 offset:38912
	ds_read_b128 v[220:223], v170 offset:39936
	global_load_lds_dwordx4 v[230:231], off
	v_lshl_add_u64 v[230:231], s[80:81], 0, v[136:137]
	s_mov_b32 m0, s74
	s_nop 0
	global_load_lds_dwordx4 v[230:231], off
	s_waitcnt vmcnt(8)
	s_waitcnt lgkmcnt(0)
	s_barrier
	s_setprio 1
	s_waitcnt lgkmcnt(0)
	v_mfma_f32_16x16x32_bf16 v[128:131], v[146:149], v[180:183], v[128:131]
	v_mfma_f32_16x16x32_bf16 v[124:127], v[154:157], v[180:183], v[124:127]
	v_mfma_f32_16x16x32_bf16 v[112:115], v[146:149], v[188:191], v[112:115]
	v_mfma_f32_16x16x32_bf16 v[108:111], v[154:157], v[188:191], v[108:111]
	v_mfma_f32_16x16x32_bf16 v[96:99], v[146:149], v[208:211], v[96:99]
	v_mfma_f32_16x16x32_bf16 v[92:95], v[154:157], v[208:211], v[92:95]
	v_mfma_f32_16x16x32_bf16 v[80:83], v[146:149], v[216:219], v[80:83]
	v_mfma_f32_16x16x32_bf16 v[76:79], v[154:157], v[216:219], v[76:79]
	v_mfma_f32_16x16x32_bf16 v[128:131], v[150:153], v[184:187], v[128:131]
	v_mfma_f32_16x16x32_bf16 v[124:127], v[158:161], v[184:187], v[124:127]
	v_mfma_f32_16x16x32_bf16 v[112:115], v[150:153], v[192:195], v[112:115]
	v_mfma_f32_16x16x32_bf16 v[108:111], v[158:161], v[192:195], v[108:111]
	v_mfma_f32_16x16x32_bf16 v[96:99], v[150:153], v[212:215], v[96:99]
	v_mfma_f32_16x16x32_bf16 v[92:95], v[158:161], v[212:215], v[92:95]
	v_mfma_f32_16x16x32_bf16 v[80:83], v[150:153], v[220:223], v[80:83]
	v_mfma_f32_16x16x32_bf16 v[76:79], v[158:161], v[220:223], v[76:79]
	v_mfma_f32_16x16x32_bf16 v[120:123], v[162:165], v[180:183], v[120:123]
	v_mfma_f32_16x16x32_bf16 v[116:119], v[172:175], v[180:183], v[116:119]
	v_mfma_f32_16x16x32_bf16 v[104:107], v[162:165], v[188:191], v[104:107]
	v_mfma_f32_16x16x32_bf16 v[100:103], v[172:175], v[188:191], v[100:103]
	v_mfma_f32_16x16x32_bf16 v[88:91], v[162:165], v[208:211], v[88:91]
	v_mfma_f32_16x16x32_bf16 v[84:87], v[172:175], v[208:211], v[84:87]
	v_mfma_f32_16x16x32_bf16 v[72:75], v[162:165], v[216:219], v[72:75]
	v_mfma_f32_16x16x32_bf16 v[68:71], v[172:175], v[216:219], v[68:71]
	v_mfma_f32_16x16x32_bf16 v[120:123], v[166:169], v[184:187], v[120:123]
	v_mfma_f32_16x16x32_bf16 v[116:119], v[176:179], v[184:187], v[116:119]
	v_mfma_f32_16x16x32_bf16 v[104:107], v[166:169], v[192:195], v[104:107]
	v_mfma_f32_16x16x32_bf16 v[100:103], v[176:179], v[192:195], v[100:103]
	v_mfma_f32_16x16x32_bf16 v[88:91], v[166:169], v[212:215], v[88:91]
	v_mfma_f32_16x16x32_bf16 v[84:87], v[176:179], v[212:215], v[84:87]
	v_mfma_f32_16x16x32_bf16 v[72:75], v[166:169], v[220:223], v[72:75]
	v_mfma_f32_16x16x32_bf16 v[68:71], v[176:179], v[220:223], v[68:71]
	s_setprio 0
	s_barrier
; #define PG8_STAGE(bufoff, gbase, voff) do { _Pragma("unroll") for (int _i = 0; _i < 2; ++_i) \
;         __builtin_amdgcn_global_load_lds((const unsigned*)((const char*)(gbase) + (voff)[_i]), (LAS unsigned*)(lds + (bufoff) + ldsw + _i * 8192), 16, 0, 0); } while (0)
; #define PG8_LDA(dst, b, h) do { _Pragma("unroll") for (int m = 0; m < 4; ++m) _Pragma("unroll") for (int k = 0; k < 2; ++k) dst[m][k] = *(const LAS bf16x8*)(lds + PG8_SA(b, h) + aoff + m * 2048 + k * 1024); } while (0)
; #define PG8_MMA(ai, bj, At, Bt) do { __builtin_amdgcn_s_setprio(1); _Pragma("unroll") for (int m = 0; m < 4; ++m) _Pragma("unroll") for (int n = 0; n < 2; ++n) _Pragma("unroll") for (int k = 0; k < 2; ++k) \
;         acc[ai][bj][m][n] = __builtin_amdgcn_mfma_f32_16x16x32_bf16(Bt[n][k], At[m][k], acc[ai][bj][m][n], 0, 0, 0); __builtin_amdgcn_s_setprio(0); } while (0)
; #define PG8_WAIT_V(n) asm volatile("s_waitcnt vmcnt(" #n ")" ::: "memory")
; #define PG8_WAIT_L(n) asm volatile("s_waitcnt lgkmcnt(" #n ")" ::: "memory")
; #define PG8_BAR __builtin_amdgcn_s_barrier()
; #define PG8_SCHED __builtin_amdgcn_sched_barrier(0)
; template <class Epi, class Sched, bool HALFN = false>
; __device__ __forceinline__ void gemm_phase(LAS unsigned char* lds, const Gemm g, const Sched& S, const Epi& E, int wave_s) {
;     ...
;             PG8_LDA(At, 1, 1); PG8_STAGE(PG8_SB(1, 0), b3, voffB); PG8_STAGE(PG8_SB(1, 1), b3 + bh1, voffB); PG8_STAGE(PG8_SA(1, 0), a3, voffA);
;             PG8_WAIT_V(8); PG8_WAIT_L(0); PG8_BAR; PG8_MMA(1, 0, At, B0); if (!HALFN) PG8_MMA(1, 1, At, B1); PG8_BAR; PG8_SCHED;
;         }
;         if (wr == 0) PG8_BAR;
	s_add_i32 s53, s53, s64
	v_lshl_add_u64 v[196:197], v[196:197], 0, s[50:51]
	s_mov_b32 m0, s53
	ds_read_b128 v[180:183], v170 offset:49152
	ds_read_b128 v[184:187], v170 offset:50176
	ds_read_b128 v[188:191], v170 offset:51200
	ds_read_b128 v[192:195], v170 offset:52224
	ds_read_b128 v[208:211], v170 offset:53248
	ds_read_b128 v[212:215], v170 offset:54272
	ds_read_b128 v[216:219], v170 offset:55296
	ds_read_b128 v[220:223], v170 offset:56320
	global_load_lds_dwordx4 v[196:197], off
	s_add_i32 m0, s53, 0x2000
	s_add_u32 s78, s78, 0x40080
	v_lshl_add_u64 v[196:197], v[224:225], 0, s[50:51]
	s_addc_u32 s79, s79, 0
	s_add_i32 s53, s66, s64
	global_load_lds_dwordx4 v[196:197], off
	v_lshl_add_u64 v[196:197], s[78:79], 0, v[134:135]
	s_mov_b32 m0, s53
	s_nop 0
	global_load_lds_dwordx4 v[196:197], off
	v_lshl_add_u64 v[196:197], s[78:79], 0, v[138:139]
	s_add_i32 m0, s53, 0x2000
	s_nop 0
	global_load_lds_dwordx4 v[196:197], off
	v_lshl_add_u64 v[196:197], v[226:227], 0, s[50:51]
	s_mov_b32 m0, s75
	s_nop 0
	global_load_lds_dwordx4 v[196:197], off
	v_lshl_add_u64 v[196:197], v[228:229], 0, s[50:51]
	s_mov_b32 m0, s88
	s_nop 0
	global_load_lds_dwordx4 v[196:197], off
	s_waitcnt vmcnt(8)
	s_waitcnt lgkmcnt(0)
	s_barrier
	s_setprio 1
	s_waitcnt lgkmcnt(0)
	v_mfma_f32_16x16x32_bf16 v[64:67], v[146:149], v[180:183], v[64:67]
	v_mfma_f32_16x16x32_bf16 v[60:63], v[154:157], v[180:183], v[60:63]
	v_mfma_f32_16x16x32_bf16 v[48:51], v[146:149], v[188:191], v[48:51]
	v_mfma_f32_16x16x32_bf16 v[44:47], v[154:157], v[188:191], v[44:47]
	v_mfma_f32_16x16x32_bf16 v[32:35], v[146:149], v[208:211], v[32:35]
	v_mfma_f32_16x16x32_bf16 v[28:31], v[154:157], v[208:211], v[28:31]
	v_mfma_f32_16x16x32_bf16 v[14:17], v[146:149], v[216:219], v[14:17]
	v_mfma_f32_16x16x32_bf16 v[10:13], v[154:157], v[216:219], v[10:13]
	v_mfma_f32_16x16x32_bf16 v[64:67], v[150:153], v[184:187], v[64:67]
	v_mfma_f32_16x16x32_bf16 v[60:63], v[158:161], v[184:187], v[60:63]
	v_mfma_f32_16x16x32_bf16 v[48:51], v[150:153], v[192:195], v[48:51]
	v_mfma_f32_16x16x32_bf16 v[44:47], v[158:161], v[192:195], v[44:47]
	v_mfma_f32_16x16x32_bf16 v[32:35], v[150:153], v[212:215], v[32:35]
	v_mfma_f32_16x16x32_bf16 v[28:31], v[158:161], v[212:215], v[28:31]
	v_mfma_f32_16x16x32_bf16 v[14:17], v[150:153], v[220:223], v[14:17]
	v_mfma_f32_16x16x32_bf16 v[10:13], v[158:161], v[220:223], v[10:13]
	v_mfma_f32_16x16x32_bf16 v[56:59], v[162:165], v[180:183], v[56:59]
	v_mfma_f32_16x16x32_bf16 v[52:55], v[172:175], v[180:183], v[52:55]
	v_mfma_f32_16x16x32_bf16 v[40:43], v[162:165], v[188:191], v[40:43]
	v_mfma_f32_16x16x32_bf16 v[36:39], v[172:175], v[188:191], v[36:39]
	v_mfma_f32_16x16x32_bf16 v[24:27], v[162:165], v[208:211], v[24:27]
	v_mfma_f32_16x16x32_bf16 v[20:23], v[172:175], v[208:211], v[20:23]
	v_mfma_f32_16x16x32_bf16 v[6:9], v[162:165], v[216:219], v[6:9]
	v_mfma_f32_16x16x32_bf16 v[2:5], v[172:175], v[216:219], v[2:5]
	v_mfma_f32_16x16x32_bf16 v[56:59], v[166:169], v[184:187], v[56:59]
	v_mfma_f32_16x16x32_bf16 v[52:55], v[176:179], v[184:187], v[52:55]
	v_mfma_f32_16x16x32_bf16 v[40:43], v[166:169], v[192:195], v[40:43]
	v_mfma_f32_16x16x32_bf16 v[36:39], v[176:179], v[192:195], v[36:39]
	v_mfma_f32_16x16x32_bf16 v[24:27], v[166:169], v[212:215], v[24:27]
	v_mfma_f32_16x16x32_bf16 v[20:23], v[176:179], v[212:215], v[20:23]
	v_mfma_f32_16x16x32_bf16 v[6:9], v[166:169], v[220:223], v[6:9]
	v_mfma_f32_16x16x32_bf16 v[2:5], v[176:179], v[220:223], v[2:5]
	s_setprio 0
	s_add_i32 s52, s52, 2
	s_add_u32 s8, s8, 0x100
	s_addc_u32 s9, s9, 0
	s_add_u32 s47, s47, 0x100
	s_addc_u32 s48, s48, 0
	s_cmp_gt_u32 s52, 13
	s_barrier
	s_cbranch_scc0 .LBB0_269
	s_and_b64 vcc, exec, s[26:27]
	s_cbranch_vccz .LBB0_272
	s_barrier

; #define PG8_STAGE(bufoff, gbase, voff) do { _Pragma("unroll") for (int _i = 0; _i < 2; ++_i) \
;         __builtin_amdgcn_global_load_lds((const unsigned*)((const char*)(gbase) + (voff)[_i]), (LAS unsigned*)(lds + (bufoff) + ldsw + _i * 8192), 16, 0, 0); } while (0)
; #define PG8_LDA(dst, b, h) do { _Pragma("unroll") for (int m = 0; m < 4; ++m) _Pragma("unroll") for (int k = 0; k < 2; ++k) dst[m][k] = *(const LAS bf16x8*)(lds + PG8_SA(b, h) + aoff + m * 2048 + k * 1024); } while (0)
; #define PG8_LDB(dst, b, h) do { _Pragma("unroll") for (int n = 0; n < 2; ++n) _Pragma("unroll") for (int k = 0; k < 2; ++k) dst[n][k] = *(const LAS bf16x8*)(lds + PG8_SB(b, h) + boff + n * 2048 + k * 1024); } while (0)
; #define PG8_MMA(ai, bj, At, Bt) do { __builtin_amdgcn_s_setprio(1); _Pragma("unroll") for (int m = 0; m < 4; ++m) _Pragma("unroll") for (int n = 0; n < 2; ++n) _Pragma("unroll") for (int k = 0; k < 2; ++k) \
;         acc[ai][bj][m][n] = __builtin_amdgcn_mfma_f32_16x16x32_bf16(Bt[n][k], At[m][k], acc[ai][bj][m][n], 0, 0, 0); __builtin_amdgcn_s_setprio(0); } while (0)
; #define PG8_WAIT_V(n) asm volatile("s_waitcnt vmcnt(" #n ")" ::: "memory")
; #define PG8_WAIT_L(n) asm volatile("s_waitcnt lgkmcnt(" #n ")" ::: "memory")
; #define PG8_BAR __builtin_amdgcn_s_barrier()
; #define PG8_SCHED __builtin_amdgcn_sched_barrier(0)
; template <class Epi, class Sched, bool HALFN = false>
; __device__ __forceinline__ void gemm_phase(LAS unsigned char* lds, const Gemm g, const Sched& S, const Epi& E, int wave_s) {
;     ...
;         for (int t = 0; t < nt; t += 2) {
;             const bool last = (t == nt - 2);
;             const char* a1 = cA + (size_t)(t + 1) * kstep;
;             const char* a2 = last ? nA : cA + (size_t)(t + 2) * kstep; const char* b2 = last ? nB : cB + (size_t)(t + 2) * kstep;
;             const char* a3 = a2 + kstep; const char* b3 = b2 + kstep;
;             PG8_LDB(B0, 0, 0); if (!HALFN) PG8_LDB(B1, 0, 1); PG8_SCHED; PG8_LDA(At, 0, 0); PG8_STAGE(PG8_SA(1, 1), a1 + hstep, voffA);
;             PG8_WAIT_V(8); PG8_WAIT_L(0); PG8_BAR; PG8_MMA(0, 0, At, B0); if (!HALFN) PG8_MMA(0, 1, At, B1); PG8_BAR; PG8_SCHED;
;             PG8_LDA(At, 0, 1); PG8_STAGE(PG8_SB(0, 0), b2, voffB); PG8_STAGE(PG8_SB(0, 1), b2 + bh1, voffB); PG8_STAGE(PG8_SA(0, 0), a2, voffA);
.LBB0_985:
	s_add_u32 s34, s6, 0xfffc0080
	s_addc_u32 s35, s7, -1
	s_add_i32 s53, 0, 0x10000
	s_cmp_eq_u32 s52, 12
	s_cselect_b32 s37, s5, s35
	s_cselect_b32 s36, s25, s34
	v_add_u32_e32 v18, s53, v1
	s_cselect_b32 s35, s23, s48
	s_cselect_b32 s34, s31, s42
	s_add_i32 s66, 0, 0x14000
	ds_read_b128 v[132:135], v18
	ds_read_b128 v[136:139], v18 offset:1024
	ds_read_b128 v[140:143], v18 offset:2048
	ds_read_b128 v[144:147], v18 offset:3072
	v_add_u32_e32 v18, s66, v1
	ds_read_b128 v[148:151], v18
	ds_read_b128 v[152:155], v18 offset:1024
	ds_read_b128 v[156:159], v18 offset:2048
	ds_read_b128 v[160:163], v18 offset:3072
	v_lshl_add_u64 v[198:199], s[6:7], 0, v[172:173]
	s_add_i32 m0, s45, 0xc000
	ds_read_b128 v[176:179], v184
	ds_read_b128 v[180:183], v184 offset:1024
	ds_read_b128 v[186:189], v184 offset:2048
	ds_read_b128 v[190:193], v184 offset:3072
	ds_read_b128 v[194:197], v184 offset:4096
	ds_read_b128 v[208:211], v184 offset:5120
	ds_read_b128 v[212:215], v184 offset:6144
	ds_read_b128 v[216:219], v184 offset:7168
	global_load_lds_dwordx4 v[198:199], off
	v_lshl_add_u64 v[198:199], s[6:7], 0, v[174:175]
	s_add_i32 m0, s45, 0xe000
	s_nop 0
	global_load_lds_dwordx4 v[198:199], off
	s_waitcnt vmcnt(8)
	s_waitcnt lgkmcnt(0)
	s_barrier
	s_setprio 1
	s_waitcnt lgkmcnt(0)
	v_mfma_f32_16x16x32_bf16 v[128:131], v[132:135], v[176:179], v[128:131]
	v_mfma_f32_16x16x32_bf16 v[124:127], v[140:143], v[176:179], v[124:127]
	v_mfma_f32_16x16x32_bf16 v[112:115], v[132:135], v[186:189], v[112:115]
	v_mfma_f32_16x16x32_bf16 v[108:111], v[140:143], v[186:189], v[108:111]
	v_mfma_f32_16x16x32_bf16 v[96:99], v[132:135], v[194:197], v[96:99]
	v_mfma_f32_16x16x32_bf16 v[92:95], v[140:143], v[194:197], v[92:95]
	v_mfma_f32_16x16x32_bf16 v[80:83], v[132:135], v[212:215], v[80:83]
	v_mfma_f32_16x16x32_bf16 v[76:79], v[140:143], v[212:215], v[76:79]
	v_mfma_f32_16x16x32_bf16 v[128:131], v[136:139], v[180:183], v[128:131]
	v_mfma_f32_16x16x32_bf16 v[124:127], v[144:147], v[180:183], v[124:127]
	v_mfma_f32_16x16x32_bf16 v[112:115], v[136:139], v[190:193], v[112:115]
	v_mfma_f32_16x16x32_bf16 v[108:111], v[144:147], v[190:193], v[108:111]
	v_mfma_f32_16x16x32_bf16 v[96:99], v[136:139], v[208:211], v[96:99]
	v_mfma_f32_16x16x32_bf16 v[92:95], v[144:147], v[208:211], v[92:95]
	v_mfma_f32_16x16x32_bf16 v[80:83], v[136:139], v[216:219], v[80:83]
	v_mfma_f32_16x16x32_bf16 v[76:79], v[144:147], v[216:219], v[76:79]
	s_setprio 0
	s_setprio 1
	v_mfma_f32_16x16x32_bf16 v[120:123], v[148:151], v[176:179], v[120:123]
	v_mfma_f32_16x16x32_bf16 v[116:119], v[156:159], v[176:179], v[116:119]
	v_mfma_f32_16x16x32_bf16 v[104:107], v[148:151], v[186:189], v[104:107]
	v_mfma_f32_16x16x32_bf16 v[100:103], v[156:159], v[186:189], v[100:103]
	v_mfma_f32_16x16x32_bf16 v[88:91], v[148:151], v[194:197], v[88:91]
	v_mfma_f32_16x16x32_bf16 v[84:87], v[156:159], v[194:197], v[84:87]
	v_mfma_f32_16x16x32_bf16 v[72:75], v[148:151], v[212:215], v[72:75]
	v_mfma_f32_16x16x32_bf16 v[68:71], v[156:159], v[212:215], v[68:71]
	v_mfma_f32_16x16x32_bf16 v[120:123], v[152:155], v[180:183], v[120:123]
	v_mfma_f32_16x16x32_bf16 v[116:119], v[160:163], v[180:183], v[116:119]
	v_mfma_f32_16x16x32_bf16 v[104:107], v[152:155], v[190:193], v[104:107]
	v_mfma_f32_16x16x32_bf16 v[100:103], v[160:163], v[190:193], v[100:103]
	v_mfma_f32_16x16x32_bf16 v[88:91], v[152:155], v[208:211], v[88:91]
	v_mfma_f32_16x16x32_bf16 v[84:87], v[160:163], v[208:211], v[84:87]
	v_mfma_f32_16x16x32_bf16 v[72:75], v[152:155], v[216:219], v[72:75]
	v_mfma_f32_16x16x32_bf16 v[68:71], v[160:163], v[216:219], v[68:71]
	s_setprio 0
	s_barrier
	s_add_i32 s53, s53, s41
	v_lshl_add_u64 v[198:199], s[34:35], 0, v[166:167]
	s_mov_b32 m0, s53
	ds_read_b128 v[176:179], v184 offset:16384
	ds_read_b128 v[180:183], v184 offset:17408
	ds_read_b128 v[186:189], v184 offset:18432
	ds_read_b128 v[190:193], v184 offset:19456
	ds_read_b128 v[194:197], v184 offset:20480
	ds_read_b128 v[208:211], v184 offset:21504
	ds_read_b128 v[212:215], v184 offset:22528
	ds_read_b128 v[216:219], v184 offset:23552
	global_load_lds_dwordx4 v[198:199], off
	s_add_i32 m0, s53, 0x2000
	s_add_u32 s76, s34, 0x40000
	v_lshl_add_u64 v[202:203], s[34:35], 0, v[170:171]
	s_addc_u32 s77, s35, 0
	s_add_i32 s53, s66, s41
	global_load_lds_dwordx4 v[202:203], off
	v_lshl_add_u64 v[220:221], s[76:77], 0, v[166:167]
	s_mov_b32 m0, s53
	v_lshl_add_u64 v[222:223], s[36:37], 0, v[168:169]
	global_load_lds_dwordx4 v[220:221], off
	v_lshl_add_u64 v[220:221], s[76:77], 0, v[170:171]
	s_add_i32 m0, s53, 0x2000
	s_nop 0
	global_load_lds_dwordx4 v[220:221], off
	v_lshl_add_u64 v[220:221], s[36:37], 0, v[164:165]
	s_mov_b32 m0, s45
	s_nop 0
	global_load_lds_dwordx4 v[220:221], off
	s_mov_b32 m0, s46
	s_nop 0
	global_load_lds_dwordx4 v[222:223], off
	s_waitcnt vmcnt(8)
	s_waitcnt lgkmcnt(0)
	s_barrier
; #define PG8_STAGE(bufoff, gbase, voff) do { _Pragma("unroll") for (int _i = 0; _i < 2; ++_i) \
;         __builtin_amdgcn_global_load_lds((const unsigned*)((const char*)(gbase) + (voff)[_i]), (LAS unsigned*)(lds + (bufoff) + ldsw + _i * 8192), 16, 0, 0); } while (0)
; #define PG8_LDA(dst, b, h) do { _Pragma("unroll") for (int m = 0; m < 4; ++m) _Pragma("unroll") for (int k = 0; k < 2; ++k) dst[m][k] = *(const LAS bf16x8*)(lds + PG8_SA(b, h) + aoff + m * 2048 + k * 1024); } while (0)
; #define PG8_LDB(dst, b, h) do { _Pragma("unroll") for (int n = 0; n < 2; ++n) _Pragma("unroll") for (int k = 0; k < 2; ++k) dst[n][k] = *(const LAS bf16x8*)(lds + PG8_SB(b, h) + boff + n * 2048 + k * 1024); } while (0)
; #define PG8_MMA(ai, bj, At, Bt) do { __builtin_amdgcn_s_setprio(1); _Pragma("unroll") for (int m = 0; m < 4; ++m) _Pragma("unroll") for (int n = 0; n < 2; ++n) _Pragma("unroll") for (int k = 0; k < 2; ++k) \
;         acc[ai][bj][m][n] = __builtin_amdgcn_mfma_f32_16x16x32_bf16(Bt[n][k], At[m][k], acc[ai][bj][m][n], 0, 0, 0); __builtin_amdgcn_s_setprio(0); } while (0)
; #define PG8_WAIT_V(n) asm volatile("s_waitcnt vmcnt(" #n ")" ::: "memory")
; #define PG8_WAIT_L(n) asm volatile("s_waitcnt lgkmcnt(" #n ")" ::: "memory")
; #define PG8_BAR __builtin_amdgcn_s_barrier()
; #define PG8_SCHED __builtin_amdgcn_sched_barrier(0)
; template <class Epi, class Sched, bool HALFN = false>
; __device__ __forceinline__ void gemm_phase(LAS unsigned char* lds, const Gemm g, const Sched& S, const Epi& E, int wave_s) {
;     ...
;             PG8_WAIT_V(8); PG8_WAIT_L(0); PG8_BAR; PG8_MMA(1, 0, At, B0); if (!HALFN) PG8_MMA(1, 1, At, B1); PG8_BAR; PG8_SCHED;
;             PG8_LDB(B0, 1, 0); if (!HALFN) PG8_LDB(B1, 1, 1); PG8_SCHED; PG8_LDA(At, 1, 0); PG8_STAGE(PG8_SA(0, 1), a2 + hstep, voffA);
;             PG8_WAIT_V(8); PG8_WAIT_L(0); PG8_BAR; PG8_MMA(0, 0, At, B0); if (!HALFN) PG8_MMA(0, 1, At, B1); PG8_BAR; PG8_SCHED;
	s_setprio 1
	s_waitcnt lgkmcnt(0)
	v_mfma_f32_16x16x32_bf16 v[64:67], v[132:135], v[176:179], v[64:67]
	v_mfma_f32_16x16x32_bf16 v[60:63], v[140:143], v[176:179], v[60:63]
	v_mfma_f32_16x16x32_bf16 v[48:51], v[132:135], v[186:189], v[48:51]
	v_mfma_f32_16x16x32_bf16 v[44:47], v[140:143], v[186:189], v[44:47]
	v_mfma_f32_16x16x32_bf16 v[32:35], v[132:135], v[194:197], v[32:35]
	v_mfma_f32_16x16x32_bf16 v[28:31], v[140:143], v[194:197], v[28:31]
	v_mfma_f32_16x16x32_bf16 v[14:17], v[132:135], v[212:215], v[14:17]
	v_mfma_f32_16x16x32_bf16 v[10:13], v[140:143], v[212:215], v[10:13]
	v_mfma_f32_16x16x32_bf16 v[64:67], v[136:139], v[180:183], v[64:67]
	v_mfma_f32_16x16x32_bf16 v[60:63], v[144:147], v[180:183], v[60:63]
	v_mfma_f32_16x16x32_bf16 v[48:51], v[136:139], v[190:193], v[48:51]
	v_mfma_f32_16x16x32_bf16 v[44:47], v[144:147], v[190:193], v[44:47]
	v_mfma_f32_16x16x32_bf16 v[32:35], v[136:139], v[208:211], v[32:35]
	v_mfma_f32_16x16x32_bf16 v[28:31], v[144:147], v[208:211], v[28:31]
	v_mfma_f32_16x16x32_bf16 v[14:17], v[136:139], v[216:219], v[14:17]
	v_mfma_f32_16x16x32_bf16 v[10:13], v[144:147], v[216:219], v[10:13]
	s_setprio 0
	s_setprio 1
	v_mfma_f32_16x16x32_bf16 v[56:59], v[148:151], v[176:179], v[56:59]
	v_mfma_f32_16x16x32_bf16 v[52:55], v[156:159], v[176:179], v[52:55]
	v_mfma_f32_16x16x32_bf16 v[40:43], v[148:151], v[186:189], v[40:43]
	v_mfma_f32_16x16x32_bf16 v[36:39], v[156:159], v[186:189], v[36:39]
	v_mfma_f32_16x16x32_bf16 v[24:27], v[148:151], v[194:197], v[24:27]
	v_mfma_f32_16x16x32_bf16 v[20:23], v[156:159], v[194:197], v[20:23]
	v_mfma_f32_16x16x32_bf16 v[6:9], v[148:151], v[212:215], v[6:9]
	v_mfma_f32_16x16x32_bf16 v[2:5], v[156:159], v[212:215], v[2:5]
	v_mfma_f32_16x16x32_bf16 v[56:59], v[152:155], v[180:183], v[56:59]
	v_mfma_f32_16x16x32_bf16 v[52:55], v[160:163], v[180:183], v[52:55]
	v_mfma_f32_16x16x32_bf16 v[40:43], v[152:155], v[190:193], v[40:43]
	v_mfma_f32_16x16x32_bf16 v[36:39], v[160:163], v[190:193], v[36:39]
	v_mfma_f32_16x16x32_bf16 v[24:27], v[152:155], v[208:211], v[24:27]
	v_mfma_f32_16x16x32_bf16 v[20:23], v[160:163], v[208:211], v[20:23]
	v_mfma_f32_16x16x32_bf16 v[6:9], v[152:155], v[216:219], v[6:9]
	v_mfma_f32_16x16x32_bf16 v[2:5], v[160:163], v[216:219], v[2:5]
	s_setprio 0
	s_barrier
	s_add_i32 s53, 0, 0x18000
	v_add_u32_e32 v18, s53, v1
	s_add_i32 s66, 0, 0x1c000
	ds_read_b128 v[132:135], v18
	ds_read_b128 v[136:139], v18 offset:1024
	ds_read_b128 v[140:143], v18 offset:2048
	ds_read_b128 v[144:147], v18 offset:3072
	v_add_u32_e32 v18, s66, v1
	ds_read_b128 v[148:151], v18
	ds_read_b128 v[152:155], v18 offset:1024
	ds_read_b128 v[156:159], v18 offset:2048
	ds_read_b128 v[160:163], v18 offset:3072
	s_add_u32 s36, s36, 0x40000
	s_addc_u32 s37, s37, 0
	s_mov_b32 m0, s47
	v_lshl_add_u64 v[224:225], s[36:37], 0, v[164:165]
	ds_read_b128 v[176:179], v184 offset:32768
	ds_read_b128 v[180:183], v184 offset:33792
	ds_read_b128 v[186:189], v184 offset:34816
	ds_read_b128 v[190:193], v184 offset:35840
	ds_read_b128 v[194:197], v184 offset:36864
	ds_read_b128 v[208:211], v184 offset:37888
	ds_read_b128 v[212:215], v184 offset:38912
	ds_read_b128 v[216:219], v184 offset:39936
	global_load_lds_dwordx4 v[224:225], off
	v_lshl_add_u64 v[224:225], s[36:37], 0, v[168:169]
	s_mov_b32 m0, s55
	s_nop 0
	global_load_lds_dwordx4 v[224:225], off
	s_waitcnt vmcnt(8)
	s_waitcnt lgkmcnt(0)
	s_barrier
	s_setprio 1
	s_waitcnt lgkmcnt(0)
	v_mfma_f32_16x16x32_bf16 v[128:131], v[132:135], v[176:179], v[128:131]
	v_mfma_f32_16x16x32_bf16 v[124:127], v[140:143], v[176:179], v[124:127]
	v_mfma_f32_16x16x32_bf16 v[112:115], v[132:135], v[186:189], v[112:115]
	v_mfma_f32_16x16x32_bf16 v[108:111], v[140:143], v[186:189], v[108:111]
	v_mfma_f32_16x16x32_bf16 v[96:99], v[132:135], v[194:197], v[96:99]
	v_mfma_f32_16x16x32_bf16 v[92:95], v[140:143], v[194:197], v[92:95]
	v_mfma_f32_16x16x32_bf16 v[80:83], v[132:135], v[212:215], v[80:83]
	v_mfma_f32_16x16x32_bf16 v[76:79], v[140:143], v[212:215], v[76:79]
	v_mfma_f32_16x16x32_bf16 v[128:131], v[136:139], v[180:183], v[128:131]
	v_mfma_f32_16x16x32_bf16 v[124:127], v[144:147], v[180:183], v[124:127]
	v_mfma_f32_16x16x32_bf16 v[112:115], v[136:139], v[190:193], v[112:115]
	v_mfma_f32_16x16x32_bf16 v[108:111], v[144:147], v[190:193], v[108:111]
	v_mfma_f32_16x16x32_bf16 v[96:99], v[136:139], v[208:211], v[96:99]
	v_mfma_f32_16x16x32_bf16 v[92:95], v[144:147], v[208:211], v[92:95]
	v_mfma_f32_16x16x32_bf16 v[80:83], v[136:139], v[216:219], v[80:83]
	v_mfma_f32_16x16x32_bf16 v[76:79], v[144:147], v[216:219], v[76:79]
	s_setprio 0
	s_setprio 1
	v_mfma_f32_16x16x32_bf16 v[120:123], v[148:151], v[176:179], v[120:123]
	v_mfma_f32_16x16x32_bf16 v[116:119], v[156:159], v[176:179], v[116:119]
	v_mfma_f32_16x16x32_bf16 v[104:107], v[148:151], v[186:189], v[104:107]
	v_mfma_f32_16x16x32_bf16 v[100:103], v[156:159], v[186:189], v[100:103]
	v_mfma_f32_16x16x32_bf16 v[88:91], v[148:151], v[194:197], v[88:91]
	v_mfma_f32_16x16x32_bf16 v[84:87], v[156:159], v[194:197], v[84:87]
	v_mfma_f32_16x16x32_bf16 v[72:75], v[148:151], v[212:215], v[72:75]
	v_mfma_f32_16x16x32_bf16 v[68:71], v[156:159], v[212:215], v[68:71]
	v_mfma_f32_16x16x32_bf16 v[120:123], v[152:155], v[180:183], v[120:123]
	v_mfma_f32_16x16x32_bf16 v[116:119], v[160:163], v[180:183], v[116:119]
	v_mfma_f32_16x16x32_bf16 v[104:107], v[152:155], v[190:193], v[104:107]
	v_mfma_f32_16x16x32_bf16 v[100:103], v[160:163], v[190:193], v[100:103]
	v_mfma_f32_16x16x32_bf16 v[88:91], v[152:155], v[208:211], v[88:91]
	v_mfma_f32_16x16x32_bf16 v[84:87], v[160:163], v[208:211], v[84:87]
	v_mfma_f32_16x16x32_bf16 v[72:75], v[152:155], v[216:219], v[72:75]
	v_mfma_f32_16x16x32_bf16 v[68:71], v[160:163], v[216:219], v[68:71]
	s_setprio 0
	s_barrier
; #define PG8_STAGE(bufoff, gbase, voff) do { _Pragma("unroll") for (int _i = 0; _i < 2; ++_i) \
;         __builtin_amdgcn_global_load_lds((const unsigned*)((const char*)(gbase) + (voff)[_i]), (LAS unsigned*)(lds + (bufoff) + ldsw + _i * 8192), 16, 0, 0); } while (0)
; #define PG8_LDA(dst, b, h) do { _Pragma("unroll") for (int m = 0; m < 4; ++m) _Pragma("unroll") for (int k = 0; k < 2; ++k) dst[m][k] = *(const LAS bf16x8*)(lds + PG8_SA(b, h) + aoff + m * 2048 + k * 1024); } while (0)
; #define PG8_MMA(ai, bj, At, Bt) do { __builtin_amdgcn_s_setprio(1); _Pragma("unroll") for (int m = 0; m < 4; ++m) _Pragma("unroll") for (int n = 0; n < 2; ++n) _Pragma("unroll") for (int k = 0; k < 2; ++k) \
;         acc[ai][bj][m][n] = __builtin_amdgcn_mfma_f32_16x16x32_bf16(Bt[n][k], At[m][k], acc[ai][bj][m][n], 0, 0, 0); __builtin_amdgcn_s_setprio(0); } while (0)
; #define PG8_WAIT_V(n) asm volatile("s_waitcnt vmcnt(" #n ")" ::: "memory")
; #define PG8_WAIT_L(n) asm volatile("s_waitcnt lgkmcnt(" #n ")" ::: "memory")
; #define PG8_BAR __builtin_amdgcn_s_barrier()
; #define PG8_SCHED __builtin_amdgcn_sched_barrier(0)
; template <class Epi, class Sched, bool HALFN = false>
; __device__ __forceinline__ void gemm_phase(LAS unsigned char* lds, const Gemm g, const Sched& S, const Epi& E, int wave_s) {
;     ...
;             PG8_LDA(At, 1, 1); PG8_STAGE(PG8_SB(1, 0), b3, voffB); PG8_STAGE(PG8_SB(1, 1), b3 + bh1, voffB); PG8_STAGE(PG8_SA(1, 0), a3, voffA);
;             PG8_WAIT_V(8); PG8_WAIT_L(0); PG8_BAR; PG8_MMA(1, 0, At, B0); if (!HALFN) PG8_MMA(1, 1, At, B1); PG8_BAR; PG8_SCHED;
;         }
;         if (wr == 0) PG8_BAR;
	s_add_i32 s36, s53, s41
	v_lshl_add_u64 v[198:199], v[198:199], 0, s[50:51]
	s_mov_b32 m0, s36
	ds_read_b128 v[176:179], v184 offset:49152
	ds_read_b128 v[180:183], v184 offset:50176
	ds_read_b128 v[186:189], v184 offset:51200
	ds_read_b128 v[190:193], v184 offset:52224
	ds_read_b128 v[194:197], v184 offset:53248
	ds_read_b128 v[208:211], v184 offset:54272
	ds_read_b128 v[212:215], v184 offset:55296
	ds_read_b128 v[216:219], v184 offset:56320
	global_load_lds_dwordx4 v[198:199], off
	s_add_i32 m0, s36, 0x2000
	s_add_u32 s34, s34, 0x40080
	v_lshl_add_u64 v[198:199], v[202:203], 0, s[50:51]
	s_addc_u32 s35, s35, 0
	s_add_i32 s36, s66, s41
	global_load_lds_dwordx4 v[198:199], off
	v_lshl_add_u64 v[198:199], s[34:35], 0, v[166:167]
	s_mov_b32 m0, s36
	s_nop 0
	global_load_lds_dwordx4 v[198:199], off
	v_lshl_add_u64 v[198:199], s[34:35], 0, v[170:171]
	s_add_i32 m0, s36, 0x2000
	s_nop 0
	global_load_lds_dwordx4 v[198:199], off
	v_lshl_add_u64 v[198:199], v[220:221], 0, s[50:51]
	s_mov_b32 m0, s64
	s_nop 0
	global_load_lds_dwordx4 v[198:199], off
	v_lshl_add_u64 v[198:199], v[222:223], 0, s[50:51]
	s_mov_b32 m0, s65
	s_nop 0
	global_load_lds_dwordx4 v[198:199], off
	s_waitcnt vmcnt(8)
	s_waitcnt lgkmcnt(0)
	s_barrier
	s_setprio 1
	s_waitcnt lgkmcnt(0)
	v_mfma_f32_16x16x32_bf16 v[64:67], v[132:135], v[176:179], v[64:67]
	v_mfma_f32_16x16x32_bf16 v[60:63], v[140:143], v[176:179], v[60:63]
	v_mfma_f32_16x16x32_bf16 v[48:51], v[132:135], v[186:189], v[48:51]
	v_mfma_f32_16x16x32_bf16 v[44:47], v[140:143], v[186:189], v[44:47]
	v_mfma_f32_16x16x32_bf16 v[32:35], v[132:135], v[194:197], v[32:35]
	v_mfma_f32_16x16x32_bf16 v[28:31], v[140:143], v[194:197], v[28:31]
	v_mfma_f32_16x16x32_bf16 v[14:17], v[132:135], v[212:215], v[14:17]
	v_mfma_f32_16x16x32_bf16 v[10:13], v[140:143], v[212:215], v[10:13]
	v_mfma_f32_16x16x32_bf16 v[64:67], v[136:139], v[180:183], v[64:67]
	v_mfma_f32_16x16x32_bf16 v[60:63], v[144:147], v[180:183], v[60:63]
	v_mfma_f32_16x16x32_bf16 v[48:51], v[136:139], v[190:193], v[48:51]
	v_mfma_f32_16x16x32_bf16 v[44:47], v[144:147], v[190:193], v[44:47]
	v_mfma_f32_16x16x32_bf16 v[32:35], v[136:139], v[208:211], v[32:35]
	v_mfma_f32_16x16x32_bf16 v[28:31], v[144:147], v[208:211], v[28:31]
	v_mfma_f32_16x16x32_bf16 v[14:17], v[136:139], v[216:219], v[14:17]
	v_mfma_f32_16x16x32_bf16 v[10:13], v[144:147], v[216:219], v[10:13]
	s_setprio 0
	s_setprio 1
	v_mfma_f32_16x16x32_bf16 v[56:59], v[148:151], v[176:179], v[56:59]
	v_mfma_f32_16x16x32_bf16 v[52:55], v[156:159], v[176:179], v[52:55]
	v_mfma_f32_16x16x32_bf16 v[40:43], v[148:151], v[186:189], v[40:43]
	v_mfma_f32_16x16x32_bf16 v[36:39], v[156:159], v[186:189], v[36:39]
	v_mfma_f32_16x16x32_bf16 v[24:27], v[148:151], v[194:197], v[24:27]
	v_mfma_f32_16x16x32_bf16 v[20:23], v[156:159], v[194:197], v[20:23]
	v_mfma_f32_16x16x32_bf16 v[6:9], v[148:151], v[212:215], v[6:9]
	v_mfma_f32_16x16x32_bf16 v[2:5], v[156:159], v[212:215], v[2:5]
	v_mfma_f32_16x16x32_bf16 v[56:59], v[152:155], v[180:183], v[56:59]
	v_mfma_f32_16x16x32_bf16 v[52:55], v[160:163], v[180:183], v[52:55]
	v_mfma_f32_16x16x32_bf16 v[40:43], v[152:155], v[190:193], v[40:43]
	v_mfma_f32_16x16x32_bf16 v[36:39], v[160:163], v[190:193], v[36:39]
	v_mfma_f32_16x16x32_bf16 v[24:27], v[152:155], v[208:211], v[24:27]
	v_mfma_f32_16x16x32_bf16 v[20:23], v[160:163], v[208:211], v[20:23]
	v_mfma_f32_16x16x32_bf16 v[6:9], v[152:155], v[216:219], v[6:9]
	v_mfma_f32_16x16x32_bf16 v[2:5], v[160:163], v[216:219], v[2:5]
	s_setprio 0
	s_add_i32 s52, s52, 2
	s_add_u32 s6, s6, 0x100
	s_addc_u32 s7, s7, 0
	s_add_u32 s42, s42, 0x100
	s_addc_u32 s48, s48, 0
	s_cmp_gt_u32 s52, 13
	s_barrier
	s_cbranch_scc0 .LBB0_985
	s_and_b64 vcc, exec, s[20:21]
	s_cbranch_vccz .LBB0_988
	s_barrier
